# baseline (speedup 1.0000x reference)
; __device__ __forceinline__ unsigned cvtpk(float lo, float hi) { f32x2_t v = {lo, hi}; bf16x2_t r = __builtin_convertvector(v, bf16x2_t); return *reinterpret_cast<unsigned*>(&r); }
; #define MFMA(a, b, c) __builtin_amdgcn_mfma_f32_16x16x32_bf16((a), (b), (c), 0, 0, 0)
; __device__ __forceinline__ void phase_dif_attn(const Params& p, char* lds) {
;     ...
;         float rsum = 0.f;
; #pragma unroll
;         for (int n = 0; n < 4; ++n)
; #pragma unroll
;           for (int j = 0; j < 4; ++j) { float pv = __builtin_amdgcn_exp2f(st[mi][n][j] - mnew); st[mi][n][j] = pv; rsum += pv; }
;         lrun[mi] = lrun[mi] * alpha + rsum;
; #pragma unroll
;         for (int ks = 0; ks < 2; ++ks) {
;           u32x4 v = {cvtpk(st[mi][2 * ks][0], st[mi][2 * ks][1]), cvtpk(st[mi][2 * ks][2], st[mi][2 * ks][3]),
;                      cvtpk(st[mi][2 * ks + 1][0], st[mi][2 * ks + 1][1]), cvtpk(st[mi][2 * ks + 1][2], st[mi][2 * ks + 1][3])};
;           pb[mi][ks] = *reinterpret_cast<bf16x8*>(&v);
;         }
;       }
; #pragma unroll
;       for (int dv = 0; dv < 8; ++dv)
; #pragma unroll
;         for (int ks = 0; ks < 2; ++ks) {
;           const char* vp = vbuf + (dv * 16 + l15) * 144 + (ks * 32 + quad * 4) * 2;
;           bf16x4 lo = *(const bf16x4*)vp, hi = *(const bf16x4*)(vp + 32);
;           bf16x8 va = {lo[0], lo[1], lo[2], lo[3], hi[0], hi[1], hi[2], hi[3]};
; #pragma unroll
;           for (int mi = 0; mi < 2; ++mi) oacc[mi][dv] = MFMA(va, pb[mi][ks], oacc[mi][dv]);
;           if (ks == 1 && (dv & 1)) __builtin_amdgcn_sched_barrier(0);
;         }
;       if (kt + 1 < ntile) lwrite((kt + 1) & 1);
;       __syncthreads();
.Lattn_back1:
	v_exp_f32_e32 v120, v120
	v_exp_f32_e32 v104, v104
	v_exp_f32_e32 v121, v121
	v_exp_f32_e32 v105, v105
	v_exp_f32_e32 v122, v122
	v_exp_f32_e32 v106, v106
	v_exp_f32_e32 v123, v123
	v_exp_f32_e32 v107, v107
	v_exp_f32_e32 v116, v116
	v_exp_f32_e32 v100, v100
	v_exp_f32_e32 v117, v117
	v_exp_f32_e32 v101, v101
	v_exp_f32_e32 v118, v118
	v_exp_f32_e32 v102, v102
	v_exp_f32_e32 v119, v119
	v_exp_f32_e32 v103, v103
	v_add_f32_e32 v165, v165, v120
	v_add_f32_e32 v164, v164, v104
	v_add_f32_e32 v165, v165, v121
	v_add_f32_e32 v164, v164, v105
	v_add_f32_e32 v165, v165, v122
	v_add_f32_e32 v164, v164, v106
	v_add_f32_e32 v165, v165, v123
	v_add_f32_e32 v164, v164, v107
	v_add_f32_e32 v165, v165, v116
	v_add_f32_e32 v164, v164, v100
	v_add_f32_e32 v165, v165, v117
	v_add_f32_e32 v164, v164, v101
	v_add_f32_e32 v165, v165, v118
	v_add_f32_e32 v164, v164, v102
	v_add_f32_e32 v165, v165, v119
	v_add_f32_e32 v164, v164, v103
	v_cvt_pk_bf16_f32 v166, v120, v121
	v_cvt_pk_bf16_f32 v167, v122, v123
	v_cvt_pk_bf16_f32 v168, v116, v117
	v_cvt_pk_bf16_f32 v169, v118, v119
	v_cvt_pk_bf16_f32 v170, v104, v105
	v_cvt_pk_bf16_f32 v171, v106, v107
	v_cvt_pk_bf16_f32 v172, v100, v101
	v_cvt_pk_bf16_f32 v173, v102, v103
	v_exp_f32_e32 v112, v112
	v_exp_f32_e32 v96, v96
	s_waitcnt lgkmcnt(12)
	v_mfma_f32_16x16x32_bf16 v[60:63], v[178:181], v[166:169], v[60:63]
	v_exp_f32_e32 v113, v113
	v_exp_f32_e32 v97, v97
	v_exp_f32_e32 v114, v114
	v_mfma_f32_16x16x32_bf16 v[56:59], v[178:181], v[170:173], v[56:59]
	v_exp_f32_e32 v98, v98
	v_exp_f32_e32 v115, v115
	ds_read_b64 v[236:237], v198 offset:24320
	ds_read_b64 v[238:239], v198 offset:24352
	s_waitcnt lgkmcnt(12)
	v_mfma_f32_16x16x32_bf16 v[48:51], v[182:185], v[166:169], v[48:51]
	v_exp_f32_e32 v99, v99
	v_exp_f32_e32 v108, v108
	v_exp_f32_e32 v92, v92
	v_mfma_f32_16x16x32_bf16 v[52:55], v[182:185], v[170:173], v[52:55]
	v_exp_f32_e32 v109, v109
	v_exp_f32_e32 v93, v93
	ds_read_b64 v[178:179], v198 offset:8256
	ds_read_b64 v[180:181], v198 offset:8288
	s_waitcnt lgkmcnt(12)
	v_mfma_f32_16x16x32_bf16 v[44:47], v[186:189], v[166:169], v[44:47]
	v_exp_f32_e32 v110, v110
	v_exp_f32_e32 v94, v94
	v_exp_f32_e32 v111, v111
	v_mfma_f32_16x16x32_bf16 v[40:43], v[186:189], v[170:173], v[40:43]
	v_exp_f32_e32 v95, v95
	v_add_f32_e32 v165, v165, v112
	ds_read_b64 v[182:183], v198 offset:10560
	ds_read_b64 v[184:185], v198 offset:10592
	s_waitcnt lgkmcnt(12)
	v_mfma_f32_16x16x32_bf16 v[36:39], v[190:193], v[166:169], v[36:39]
	v_add_f32_e32 v164, v164, v96
	v_add_f32_e32 v165, v165, v113
	v_add_f32_e32 v164, v164, v97
	v_mfma_f32_16x16x32_bf16 v[32:35], v[190:193], v[170:173], v[32:35]
	v_add_f32_e32 v165, v165, v114
	v_add_f32_e32 v164, v164, v98
	ds_read_b64 v[186:187], v198 offset:12864
	ds_read_b64 v[188:189], v198 offset:12896
	s_waitcnt lgkmcnt(12)
	v_mfma_f32_16x16x32_bf16 v[28:31], v[194:197], v[166:169], v[28:31]
	v_add_f32_e32 v165, v165, v115
	v_add_f32_e32 v164, v164, v99
	v_add_f32_e32 v165, v165, v108
	v_mfma_f32_16x16x32_bf16 v[24:27], v[194:197], v[170:173], v[24:27]
	v_add_f32_e32 v164, v164, v92
	v_add_f32_e32 v165, v165, v109
	ds_read_b64 v[190:191], v198 offset:15168
	ds_read_b64 v[192:193], v198 offset:15200
	s_waitcnt lgkmcnt(12)
	v_mfma_f32_16x16x32_bf16 v[20:23], v[228:231], v[166:169], v[20:23]
	v_add_f32_e32 v164, v164, v93
	v_add_f32_e32 v165, v165, v110
	v_add_f32_e32 v164, v164, v94
	v_mfma_f32_16x16x32_bf16 v[16:19], v[228:231], v[170:173], v[16:19]
	v_add_f32_e32 v165, v165, v111
	v_add_f32_e32 v164, v164, v95
	ds_read_b64 v[194:195], v198 offset:17472
	ds_read_b64 v[196:197], v198 offset:17504
	s_waitcnt lgkmcnt(12)
	v_mfma_f32_16x16x32_bf16 v[12:15], v[232:235], v[166:169], v[12:15]
	v_cvt_pk_bf16_f32 v174, v112, v113
	v_cvt_pk_bf16_f32 v175, v114, v115
	v_cvt_pk_bf16_f32 v176, v108, v109
	v_mfma_f32_16x16x32_bf16 v[8:11], v[232:235], v[170:173], v[8:11]
	v_cvt_pk_bf16_f32 v177, v110, v111
	v_cvt_pk_bf16_f32 v248, v96, v97
	ds_read_b64 v[228:229], v198 offset:19776
	ds_read_b64 v[230:231], v198 offset:19808
	s_waitcnt lgkmcnt(12)
	v_mfma_f32_16x16x32_bf16 v[4:7], v[236:239], v[166:169], v[4:7]
	v_cvt_pk_bf16_f32 v249, v98, v99
	v_cvt_pk_bf16_f32 v250, v92, v93
	v_cvt_pk_bf16_f32 v251, v94, v95
	v_mfma_f32_16x16x32_bf16 v[0:3], v[236:239], v[170:173], v[0:3]
	ds_read_b64 v[232:233], v198 offset:22080
	ds_read_b64 v[234:235], v198 offset:22112
	s_add_i32 s6, s6, 1
	s_waitcnt lgkmcnt(12)
	v_mfma_f32_16x16x32_bf16 v[60:63], v[178:181], v[174:177], v[60:63]
	v_mfma_f32_16x16x32_bf16 v[56:59], v[178:181], v[248:251], v[56:59]
	ds_read_b64 v[236:237], v198 offset:24384
	ds_read_b64 v[238:239], v198 offset:24416
	s_waitcnt lgkmcnt(12)
	v_mfma_f32_16x16x32_bf16 v[48:51], v[182:185], v[174:177], v[48:51]
	v_mfma_f32_16x16x32_bf16 v[52:55], v[182:185], v[248:251], v[52:55]
	s_waitcnt lgkmcnt(10)
	v_mfma_f32_16x16x32_bf16 v[44:47], v[186:189], v[174:177], v[44:47]
	v_mfma_f32_16x16x32_bf16 v[40:43], v[186:189], v[248:251], v[40:43]
	s_bitcmp1_b32 s6, 0
	s_cselect_b32 s8, 0x6800, 0
	s_add_i32 s8, s8, 0
	v_add_u32_e32 v92, s8, v149
	v_add3_u32 v92, v92, v151, v152
	s_waitcnt vmcnt(2)
	ds_write_b128 v92, v[80:83]
	v_add3_u32 v80, s8, v153, v154
	s_add_i32 s7, s7, 64
	s_waitcnt vmcnt(1)
	ds_write_b128 v80, v[84:87] offset:8192
	v_add3_u32 v80, s8, v155, v154
	s_waitcnt vmcnt(0)
	ds_write_b128 v80, v[88:91] offset:8192
	s_waitcnt lgkmcnt(11)
	v_mfma_f32_16x16x32_bf16 v[36:39], v[190:193], v[174:177], v[36:39]
	v_mfma_f32_16x16x32_bf16 v[32:35], v[190:193], v[248:251], v[32:35]
	s_waitcnt lgkmcnt(9)
	v_mfma_f32_16x16x32_bf16 v[28:31], v[194:197], v[174:177], v[28:31]
	v_mfma_f32_16x16x32_bf16 v[24:27], v[194:197], v[248:251], v[24:27]
	s_waitcnt lgkmcnt(7)
	v_mfma_f32_16x16x32_bf16 v[20:23], v[228:231], v[174:177], v[20:23]
	v_mfma_f32_16x16x32_bf16 v[16:19], v[228:231], v[248:251], v[16:19]
	s_waitcnt lgkmcnt(5)
	v_mfma_f32_16x16x32_bf16 v[12:15], v[232:235], v[174:177], v[12:15]
	v_mfma_f32_16x16x32_bf16 v[8:11], v[232:235], v[248:251], v[8:11]
	s_waitcnt lgkmcnt(3)
	v_mfma_f32_16x16x32_bf16 v[4:7], v[236:239], v[174:177], v[4:7]
	v_mfma_f32_16x16x32_bf16 v[0:3], v[236:239], v[248:251], v[0:3]
	s_cmp_eq_u32 s5, s6
	s_waitcnt lgkmcnt(0)
	s_barrier
	s_cbranch_scc0 .LBB0_501
